# attention row-max reductions use v_permlane16/32_swap (VALU) instead of ds_bpermute LDS round trips
# speedup vs baseline: 1.1147x; 1.0101x over previous
.LBB0_361:
	s_add_i32 s5, s4, -1
	s_bitcmp1_b32 s5, 0
	s_cselect_b32 s30, 0x5c00, 0
	s_bitcmp1_b32 s4, 0
	s_cselect_b32 s6, 0x5c00, 0
	v_add_u32_e32 v212, s30, v185
	v_add_u32_e32 v211, 0x1a00, v212
	v_add_u32_e32 v205, v211, v210
	v_add_u32_e32 v204, v212, v210
	ds_read_b128 v[136:139], v205
	ds_read_b128 v[140:143], v204
	ds_read_b128 v[144:147], v204 offset:64
	v_lshlrev_b32_e32 v132, 1, v178
	v_lshlrev_b32_e32 v133, 1, v152
	v_add3_u32 v132, s6, v132, v133
	s_waitcnt vmcnt(4)
	ds_write_b128 v132, v[112:115]
	v_lshlrev_b32_e32 v112, 1, v179
	v_lshlrev_b32_e32 v113, 1, v154
	v_add3_u32 v112, s6, v112, v113
	s_waitcnt vmcnt(3)
	ds_write_b128 v112, v[116:119]
	v_lshlrev_b32_e32 v112, 1, v180
	v_lshlrev_b32_e32 v113, 1, v156
	v_add3_u32 v112, s6, v112, v113
	s_waitcnt vmcnt(2)
	ds_write_b128 v112, v[128:131]
	v_lshlrev_b32_e32 v112, 1, v181
	v_lshlrev_b32_e32 v113, 1, v158
	v_add3_u32 v112, s6, v112, v113
	s_waitcnt vmcnt(1)
	ds_write_b128 v112, v[124:127] offset:13312
	v_lshlrev_b32_e32 v112, 1, v182
	v_lshlrev_b32_e32 v113, 1, v164
	s_min_u32 s5, s5, 5
	v_add3_u32 v112, s6, v112, v113
	s_lshl_b32 s6, s5, 5
	s_add_i32 s31, s6, 64
	s_waitcnt vmcnt(0)
	ds_write_b128 v112, v[120:123] offset:13312
	v_add_u32_e32 v112, s31, v161
	v_add_u32_e32 v114, s31, v174
	v_add_u32_e32 v120, s31, v175
	v_mad_i64_i32 v[112:113], s[6:7], v112, s18, v[168:169]
	v_mad_i64_i32 v[116:117], s[6:7], v114, s18, v[170:171]
	v_mad_i64_i32 v[120:121], s[6:7], v120, s18, v[172:173]
	s_lshl_b32 s36, s5, 6
	global_load_dwordx4 v[112:115], v[112:113], off
	s_nop 0
	global_load_dwordx4 v[116:119], v[116:117], off
	v_lshl_add_u64 v[122:123], v[162:163], 0, s[36:37]
	global_load_dwordx4 v[128:131], v[120:121], off
	global_load_dwordx4 v[124:127], v[122:123], off offset:128
	v_lshl_add_u64 v[120:121], v[166:167], 0, s[36:37]
	global_load_dwordx4 v[120:123], v[120:121], off offset:128
	v_xor_b32_e32 v132, 0x80000000, v187
	v_mov_b32_e32 v133, v132
	v_mov_b32_e32 v134, v132
	v_mov_b32_e32 v135, v132
	v_xor_b32_e32 v190, 0x80000000, v186
	v_mov_b32_e32 v191, v190
	v_mov_b32_e32 v192, v190
	v_mov_b32_e32 v193, v190
	s_waitcnt lgkmcnt(6)
	v_mfma_f32_16x16x32_bf16 v[194:197], v[140:143], v[40:43], v[132:135]
	v_mfma_f32_16x16x32_bf16 v[140:143], v[140:143], v[44:47], v[190:193]
	ds_read_b128 v[198:201], v205 offset:64
	v_mfma_f32_16x16x32_bf16 v[132:135], v[136:139], v[40:43], v[132:135]
	v_mfma_f32_16x16x32_bf16 v[136:139], v[136:139], v[44:47], v[190:193]
	s_nop 2
	ds_read_b128 v[190:193], v204 offset:128
	s_waitcnt lgkmcnt(2)
	v_mfma_f32_16x16x32_bf16 v[140:143], v[144:147], v[36:39], v[140:143]
	v_mfma_f32_16x16x32_bf16 v[194:197], v[144:147], v[32:35], v[194:197]
	ds_read_b128 v[144:147], v205 offset:128
	s_waitcnt lgkmcnt(2)
	v_mfma_f32_16x16x32_bf16 v[132:135], v[198:201], v[32:35], v[132:135]
	v_mfma_f32_16x16x32_bf16 v[136:139], v[198:201], v[36:39], v[136:139]
	ds_read_b128 v[198:201], v204 offset:192
	s_waitcnt lgkmcnt(2)
	v_mfma_f32_16x16x32_bf16 v[140:143], v[190:193], v[28:31], v[140:143]
	v_mfma_f32_16x16x32_bf16 v[194:197], v[190:193], v[24:27], v[194:197]
	ds_read_b128 v[190:193], v205 offset:192
	s_waitcnt lgkmcnt(2)
	v_mfma_f32_16x16x32_bf16 v[132:135], v[144:147], v[24:27], v[132:135]
	v_mfma_f32_16x16x32_bf16 v[136:139], v[144:147], v[28:31], v[136:139]
	ds_read_b128 v[144:147], v204 offset:256
	s_waitcnt lgkmcnt(2)
	v_mfma_f32_16x16x32_bf16 v[140:143], v[198:201], v[20:23], v[140:143]
	v_mfma_f32_16x16x32_bf16 v[194:197], v[198:201], v[16:19], v[194:197]
	ds_read_b128 v[198:201], v205 offset:256
	s_waitcnt lgkmcnt(2)
	v_mfma_f32_16x16x32_bf16 v[132:135], v[190:193], v[16:19], v[132:135]
	v_mfma_f32_16x16x32_bf16 v[136:139], v[190:193], v[20:23], v[136:139]
	ds_read_b128 v[190:193], v204 offset:320
	s_waitcnt lgkmcnt(2)
	v_mfma_f32_16x16x32_bf16 v[140:143], v[144:147], v[12:15], v[140:143]
	v_mfma_f32_16x16x32_bf16 v[194:197], v[144:147], v[4:7], v[194:197]
	ds_read_b128 v[204:207], v205 offset:320
	s_waitcnt lgkmcnt(2)
	v_mfma_f32_16x16x32_bf16 v[132:135], v[198:201], v[4:7], v[132:135]
	v_mfma_f32_16x16x32_bf16 v[198:201], v[198:201], v[12:15], v[136:139]
	s_waitcnt lgkmcnt(1)
	v_mfma_f32_16x16x32_bf16 v[144:147], v[190:193], v[0:3], v[194:197]
	v_mfma_f32_16x16x32_bf16 v[136:139], v[190:193], v[8:11], v[140:143]
	s_waitcnt lgkmcnt(0)
	v_mfma_f32_16x16x32_bf16 v[140:143], v[204:207], v[0:3], v[132:135]
	v_mfma_f32_16x16x32_bf16 v[132:135], v[204:207], v[8:11], v[198:201]
	s_nop 3
	v_max_f32_e32 v190, v145, v145
	v_max_f32_e32 v191, v144, v144
	v_max_f32_e32 v198, v137, v137
	v_max_f32_e32 v199, v136, v136
	v_max_f32_e32 v190, v191, v190
	v_max_f32_e32 v198, v199, v198
	v_max3_f32 v190, v190, v146, v147
	v_max3_f32 v198, v198, v138, v139
	v_max3_f32 v190, v190, v140, v141
	v_max3_f32 v198, v198, v132, v133
	v_max3_f32 v190, v190, v142, v143
	v_max3_f32 v198, v198, v134, v135
	v_mov_b32_e32 v191, v190
	v_mov_b32_e32 v199, v198
	s_nop 1
	v_permlane16_swap_b32_e32 v191, v190
	v_permlane16_swap_b32_e32 v199, v198
	v_max_f32_e32 v190, v190, v191
	v_max_f32_e32 v198, v198, v199
	v_mov_b32_e32 v191, v190
	v_mov_b32_e32 v199, v198
	s_nop 1
	v_permlane32_swap_b32_e32 v191, v190
	v_permlane32_swap_b32_e32 v199, v198
	v_max_f32_e32 v213, v190, v191
	v_max_f32_e32 v200, v198, v199
	v_cmp_lt_f32_e32 vcc, s79, v213
	s_cbranch_vccz .LBB0_363
	s_nop 0
	v_cndmask_b32_e32 v191, 0, v213, vcc
	v_exp_f32_e64 v190, -v191
	v_add_f32_e32 v187, v187, v191
	v_sub_f32_e32 v144, v144, v191
	v_sub_f32_e32 v145, v145, v191
	v_pk_mul_f32 v[70:71], v[70:71], v[190:191] op_sel_hi:[1,0]
	v_pk_mul_f32 v[68:69], v[68:69], v[190:191] op_sel_hi:[1,0]
	v_pk_mul_f32 v[74:75], v[74:75], v[190:191] op_sel_hi:[1,0]
	v_pk_mul_f32 v[72:73], v[72:73], v[190:191] op_sel_hi:[1,0]
	v_pk_mul_f32 v[78:79], v[78:79], v[190:191] op_sel_hi:[1,0]
	v_pk_mul_f32 v[76:77], v[76:77], v[190:191] op_sel_hi:[1,0]
	v_pk_mul_f32 v[102:103], v[102:103], v[190:191] op_sel_hi:[1,0]
	v_pk_mul_f32 v[100:101], v[100:101], v[190:191] op_sel_hi:[1,0]
	v_pk_mul_f32 v[82:83], v[82:83], v[190:191] op_sel_hi:[1,0]
	v_pk_mul_f32 v[80:81], v[80:81], v[190:191] op_sel_hi:[1,0]
	v_pk_mul_f32 v[106:107], v[106:107], v[190:191] op_sel_hi:[1,0]
	v_pk_mul_f32 v[104:105], v[104:105], v[190:191] op_sel_hi:[1,0]
	v_pk_mul_f32 v[110:111], v[110:111], v[190:191] op_sel_hi:[1,0]
	v_pk_mul_f32 v[108:109], v[108:109], v[190:191] op_sel_hi:[1,0]
	v_pk_mul_f32 v[86:87], v[86:87], v[190:191] op_sel_hi:[1,0]
	v_pk_mul_f32 v[84:85], v[84:85], v[190:191] op_sel_hi:[1,0]
	v_mul_f32_e32 v165, v165, v190
	v_sub_f32_e32 v146, v146, v191
	v_sub_f32_e32 v147, v147, v191
	v_sub_f32_e32 v140, v140, v191
	v_sub_f32_e32 v141, v141, v191
	v_sub_f32_e32 v142, v142, v191
	v_sub_f32_e32 v143, v143, v191

.LBB0_377:
	s_add_i32 s5, s4, -1
	s_bitcmp1_b32 s5, 0
	s_cselect_b32 s30, 0x5c00, 0
	s_bitcmp1_b32 s4, 0
	s_cselect_b32 s6, 0x5c00, 0
	v_add_u32_e32 v212, s30, v185
	v_add_u32_e32 v211, 0x1a00, v212
	v_add_u32_e32 v205, v211, v210
	v_add_u32_e32 v204, v212, v210
	ds_read_b128 v[136:139], v205
	ds_read_b128 v[140:143], v204
	ds_read_b128 v[144:147], v204 offset:64
	v_lshlrev_b32_e32 v132, 1, v178
	v_lshlrev_b32_e32 v133, 1, v152
	v_add3_u32 v132, s6, v132, v133
	s_waitcnt vmcnt(4)
	ds_write_b128 v132, v[112:115]
	v_lshlrev_b32_e32 v112, 1, v179
	v_lshlrev_b32_e32 v113, 1, v154
	v_add3_u32 v112, s6, v112, v113
	s_waitcnt vmcnt(3)
	ds_write_b128 v112, v[116:119]
	v_lshlrev_b32_e32 v112, 1, v180
	v_lshlrev_b32_e32 v113, 1, v156
	v_add3_u32 v112, s6, v112, v113
	s_waitcnt vmcnt(2)
	ds_write_b128 v112, v[128:131]
	v_lshlrev_b32_e32 v112, 1, v181
	v_lshlrev_b32_e32 v113, 1, v158
	v_add3_u32 v112, s6, v112, v113
	s_waitcnt vmcnt(1)
	ds_write_b128 v112, v[124:127] offset:13312
	v_lshlrev_b32_e32 v112, 1, v182
	v_lshlrev_b32_e32 v113, 1, v164
	s_min_u32 s5, s5, 37
	v_add3_u32 v112, s6, v112, v113
	s_lshl_b32 s6, s5, 5
	s_add_i32 s31, s6, 64
	s_waitcnt vmcnt(0)
	ds_write_b128 v112, v[120:123] offset:13312
	v_add_u32_e32 v112, s31, v161
	v_add_u32_e32 v114, s31, v174
	v_add_u32_e32 v120, s31, v175
	v_mad_i64_i32 v[112:113], s[6:7], v112, s18, v[168:169]
	v_mad_i64_i32 v[116:117], s[6:7], v114, s18, v[170:171]
	v_mad_i64_i32 v[120:121], s[6:7], v120, s18, v[172:173]
	s_lshl_b32 s36, s5, 6
	global_load_dwordx4 v[112:115], v[112:113], off
	s_nop 0
	global_load_dwordx4 v[116:119], v[116:117], off
	v_lshl_add_u64 v[122:123], v[162:163], 0, s[36:37]
	global_load_dwordx4 v[128:131], v[120:121], off
	global_load_dwordx4 v[124:127], v[122:123], off offset:128
	v_lshl_add_u64 v[120:121], v[166:167], 0, s[36:37]
	global_load_dwordx4 v[120:123], v[120:121], off offset:128
	v_xor_b32_e32 v132, 0x80000000, v187
	v_mov_b32_e32 v133, v132
	v_mov_b32_e32 v134, v132
	v_mov_b32_e32 v135, v132
	v_xor_b32_e32 v190, 0x80000000, v186
	v_mov_b32_e32 v191, v190
	v_mov_b32_e32 v192, v190
	v_mov_b32_e32 v193, v190
	s_waitcnt lgkmcnt(6)
	v_mfma_f32_16x16x32_bf16 v[194:197], v[140:143], v[40:43], v[132:135]
	v_mfma_f32_16x16x32_bf16 v[140:143], v[140:143], v[44:47], v[190:193]
	ds_read_b128 v[198:201], v205 offset:64
	v_mfma_f32_16x16x32_bf16 v[132:135], v[136:139], v[40:43], v[132:135]
	v_mfma_f32_16x16x32_bf16 v[136:139], v[136:139], v[44:47], v[190:193]
	s_nop 2
	ds_read_b128 v[190:193], v204 offset:128
	s_waitcnt lgkmcnt(2)
	v_mfma_f32_16x16x32_bf16 v[140:143], v[144:147], v[36:39], v[140:143]
	v_mfma_f32_16x16x32_bf16 v[194:197], v[144:147], v[32:35], v[194:197]
	ds_read_b128 v[144:147], v205 offset:128
	s_waitcnt lgkmcnt(2)
	v_mfma_f32_16x16x32_bf16 v[132:135], v[198:201], v[32:35], v[132:135]
	v_mfma_f32_16x16x32_bf16 v[136:139], v[198:201], v[36:39], v[136:139]
	ds_read_b128 v[198:201], v204 offset:192
	s_waitcnt lgkmcnt(2)
	v_mfma_f32_16x16x32_bf16 v[140:143], v[190:193], v[28:31], v[140:143]
	v_mfma_f32_16x16x32_bf16 v[194:197], v[190:193], v[24:27], v[194:197]
	ds_read_b128 v[190:193], v205 offset:192
	s_waitcnt lgkmcnt(2)
	v_mfma_f32_16x16x32_bf16 v[132:135], v[144:147], v[24:27], v[132:135]
	v_mfma_f32_16x16x32_bf16 v[136:139], v[144:147], v[28:31], v[136:139]
	ds_read_b128 v[144:147], v204 offset:256
	s_waitcnt lgkmcnt(2)
	v_mfma_f32_16x16x32_bf16 v[140:143], v[198:201], v[20:23], v[140:143]
	v_mfma_f32_16x16x32_bf16 v[194:197], v[198:201], v[16:19], v[194:197]
	ds_read_b128 v[198:201], v205 offset:256
	s_waitcnt lgkmcnt(2)
	v_mfma_f32_16x16x32_bf16 v[132:135], v[190:193], v[16:19], v[132:135]
	v_mfma_f32_16x16x32_bf16 v[136:139], v[190:193], v[20:23], v[136:139]
	ds_read_b128 v[190:193], v204 offset:320
	s_waitcnt lgkmcnt(2)
	v_mfma_f32_16x16x32_bf16 v[140:143], v[144:147], v[12:15], v[140:143]
	v_mfma_f32_16x16x32_bf16 v[194:197], v[144:147], v[4:7], v[194:197]
	ds_read_b128 v[204:207], v205 offset:320
	s_waitcnt lgkmcnt(2)
	v_mfma_f32_16x16x32_bf16 v[132:135], v[198:201], v[4:7], v[132:135]
	v_mfma_f32_16x16x32_bf16 v[198:201], v[198:201], v[12:15], v[136:139]
	s_waitcnt lgkmcnt(1)
	v_mfma_f32_16x16x32_bf16 v[144:147], v[190:193], v[0:3], v[194:197]
	v_mfma_f32_16x16x32_bf16 v[136:139], v[190:193], v[8:11], v[140:143]
	s_waitcnt lgkmcnt(0)
	v_mfma_f32_16x16x32_bf16 v[140:143], v[204:207], v[0:3], v[132:135]
	v_mfma_f32_16x16x32_bf16 v[132:135], v[204:207], v[8:11], v[198:201]
	s_nop 3
	v_max_f32_e32 v190, v145, v145
	v_max_f32_e32 v191, v144, v144
	v_max_f32_e32 v198, v137, v137
	v_max_f32_e32 v199, v136, v136
	v_max_f32_e32 v190, v191, v190
	v_max_f32_e32 v198, v199, v198
	v_max3_f32 v190, v190, v146, v147
	v_max3_f32 v198, v198, v138, v139
	v_max3_f32 v190, v190, v140, v141
	v_max3_f32 v198, v198, v132, v133
	v_max3_f32 v190, v190, v142, v143
	v_max3_f32 v198, v198, v134, v135
	v_mov_b32_e32 v191, v190
	v_mov_b32_e32 v199, v198
	s_nop 1
	v_permlane16_swap_b32_e32 v191, v190
	v_permlane16_swap_b32_e32 v199, v198
	v_max_f32_e32 v190, v190, v191
	v_max_f32_e32 v198, v198, v199
	v_mov_b32_e32 v191, v190
	v_mov_b32_e32 v199, v198
	s_nop 1
	v_permlane32_swap_b32_e32 v191, v190
	v_permlane32_swap_b32_e32 v199, v198
	v_max_f32_e32 v213, v190, v191
	v_max_f32_e32 v200, v198, v199
	v_cmp_lt_f32_e32 vcc, s79, v213
	s_cbranch_vccz .LBB0_379
	s_nop 0
	v_cndmask_b32_e32 v191, 0, v213, vcc
	v_exp_f32_e64 v190, -v191
	v_add_f32_e32 v187, v187, v191
	v_sub_f32_e32 v144, v144, v191
	v_sub_f32_e32 v145, v145, v191
	v_pk_mul_f32 v[70:71], v[70:71], v[190:191] op_sel_hi:[1,0]
	v_pk_mul_f32 v[68:69], v[68:69], v[190:191] op_sel_hi:[1,0]
	v_pk_mul_f32 v[74:75], v[74:75], v[190:191] op_sel_hi:[1,0]
	v_pk_mul_f32 v[72:73], v[72:73], v[190:191] op_sel_hi:[1,0]
	v_pk_mul_f32 v[78:79], v[78:79], v[190:191] op_sel_hi:[1,0]
	v_pk_mul_f32 v[76:77], v[76:77], v[190:191] op_sel_hi:[1,0]
	v_pk_mul_f32 v[102:103], v[102:103], v[190:191] op_sel_hi:[1,0]
	v_pk_mul_f32 v[100:101], v[100:101], v[190:191] op_sel_hi:[1,0]
	v_pk_mul_f32 v[82:83], v[82:83], v[190:191] op_sel_hi:[1,0]
	v_pk_mul_f32 v[80:81], v[80:81], v[190:191] op_sel_hi:[1,0]
	v_pk_mul_f32 v[106:107], v[106:107], v[190:191] op_sel_hi:[1,0]
	v_pk_mul_f32 v[104:105], v[104:105], v[190:191] op_sel_hi:[1,0]
	v_pk_mul_f32 v[110:111], v[110:111], v[190:191] op_sel_hi:[1,0]
	v_pk_mul_f32 v[108:109], v[108:109], v[190:191] op_sel_hi:[1,0]
	v_pk_mul_f32 v[86:87], v[86:87], v[190:191] op_sel_hi:[1,0]
	v_pk_mul_f32 v[84:85], v[84:85], v[190:191] op_sel_hi:[1,0]
	v_mul_f32_e32 v165, v165, v190
	v_sub_f32_e32 v146, v146, v191
	v_sub_f32_e32 v147, v147, v191
	v_sub_f32_e32 v140, v140, v191
	v_sub_f32_e32 v141, v141, v191
	v_sub_f32_e32 v142, v142, v191
	v_sub_f32_e32 v143, v143, v191

.LBB0_1040:
	s_add_i32 s14, s12, -1
	s_bitcmp1_b32 s14, 0
	s_cselect_b32 s13, 0x9000, 0
	s_bitcmp1_b32 s12, 0
	s_cselect_b32 s15, 0x9000, 0
	v_lshlrev_b32_e32 v112, 1, v151
	v_lshlrev_b32_e32 v113, 1, v146
	v_add3_u32 v112, s15, v112, v113
	s_waitcnt vmcnt(7)
	ds_write_b128 v112, v[16:19]
	v_lshlrev_b32_e32 v16, 1, v153
	v_lshlrev_b32_e32 v17, 1, v152
	v_add3_u32 v16, s15, v16, v17
	s_waitcnt vmcnt(5)
	ds_write_b128 v16, v[20:23]
	v_lshlrev_b32_e32 v16, 1, v155
	v_lshlrev_b32_e32 v17, 1, v156
	v_add3_u32 v16, s15, v16, v17
	ds_write_b128 v16, v[32:35]
	v_lshlrev_b32_e32 v16, 1, v157
	v_lshlrev_b32_e32 v17, 1, v160
	v_add3_u32 v16, s15, v16, v17
	s_waitcnt vmcnt(4)
	ds_write_b128 v16, v[44:47]
	v_lshlrev_b32_e32 v16, 1, v159
	v_lshlrev_b32_e32 v17, 1, v162
	v_add3_u32 v16, s15, v16, v17
	s_waitcnt vmcnt(3)
	ds_write_b128 v16, v[60:63] offset:18432
	v_lshlrev_b32_e32 v16, 1, v161
	v_lshlrev_b32_e32 v17, 1, v166
	v_add3_u32 v16, s15, v16, v17
	s_waitcnt vmcnt(2)
	ds_write_b128 v16, v[52:55] offset:18432
	v_lshlrev_b32_e32 v16, 1, v163
	v_lshlrev_b32_e32 v17, 1, v170
	v_add3_u32 v16, s15, v16, v17
	s_waitcnt vmcnt(1)
	ds_write_b128 v16, v[56:59] offset:18432
	v_lshlrev_b32_e32 v16, 1, v167
	v_lshlrev_b32_e32 v17, 1, v174
	s_min_u32 s14, s14, 17
	v_add3_u32 v16, s15, v16, v17
	s_lshl_b32 s15, s14, 6
	s_addk_i32 s15, 0x80
	s_waitcnt vmcnt(0)
	ds_write_b128 v16, v[48:51] offset:18432
	v_add_u32_e32 v16, s15, v144
	v_add_u32_e32 v18, s15, v150
	v_add_u32_e32 v32, s15, v154
	v_add_u32_e32 v34, s15, v158
	v_ashrrev_i32_e32 v17, 31, v16
	v_ashrrev_i32_e32 v19, 31, v18
	v_ashrrev_i32_e32 v33, 31, v32
	v_ashrrev_i32_e32 v35, 31, v34
	v_lshlrev_b64 v[16:17], 11, v[16:17]
	v_lshlrev_b64 v[18:19], 11, v[18:19]
	v_lshlrev_b64 v[32:33], 11, v[32:33]
	v_lshlrev_b64 v[34:35], 11, v[34:35]
	s_lshl_b32 s36, s14, 7
	v_lshl_add_u64 v[16:17], v[180:181], 0, v[16:17]
	v_lshl_add_u64 v[20:21], v[182:183], 0, v[18:19]
	v_lshl_add_u64 v[32:33], v[184:185], 0, v[32:33]
	v_lshl_add_u64 v[44:45], v[186:187], 0, v[34:35]
	v_lshl_add_u64 v[48:49], v[164:165], 0, s[36:37]
	v_lshl_add_u64 v[50:51], v[168:169], 0, s[36:37]
	global_load_dwordx4 v[16:19], v[16:17], off
	s_nop 0
	global_load_dwordx4 v[20:23], v[20:21], off
	s_nop 0
	global_load_dwordx4 v[32:35], v[32:33], off
	s_nop 0
	global_load_dwordx4 v[44:47], v[44:45], off
	s_nop 0
	global_load_dwordx4 v[60:63], v[48:49], off offset:256
	global_load_dwordx4 v[52:55], v[50:51], off offset:256
	v_lshl_add_u64 v[48:49], v[172:173], 0, s[36:37]
	v_lshl_add_u64 v[50:51], v[178:179], 0, s[36:37]
	global_load_dwordx4 v[56:59], v[48:49], off offset:256
	s_nop 0
	global_load_dwordx4 v[48:51], v[50:51], off offset:256
	v_lshlrev_b32_e32 v116, 1, v214
	v_add3_u32 v217, s13, v211, v116
	ds_read_b128 v[226:229], v217
	ds_read_b128 v[230:233], v217 offset:128
	ds_read_b128 v[234:237], v217 offset:4608
	ds_read_b128 v[242:245], v217 offset:4736
	ds_read_b128 v[246:249], v217 offset:9216
	v_xor_b32_e32 v112, 0x80000000, v213
	v_xor_b32_e32 v128, 0x80000000, v212
	v_mov_b32_e32 v113, v112
	v_mov_b32_e32 v114, v112
	v_mov_b32_e32 v115, v112
	v_mov_b32_e32 v129, v128
	v_mov_b32_e32 v130, v128
	v_mov_b32_e32 v131, v128
	ds_read_b128 v[204:207], v217 offset:9344
	s_waitcnt lgkmcnt(5)
	v_mfma_f32_16x16x32_bf16 v[116:119], v[226:229], v[12:15], v[112:115]
	ds_read_b128 v[226:229], v217 offset:13824
	s_waitcnt lgkmcnt(5)
	v_mfma_f32_16x16x32_bf16 v[120:123], v[230:233], v[8:11], v[128:131]
	ds_read_b128 v[230:233], v217 offset:13952
	s_waitcnt lgkmcnt(5)
	v_mfma_f32_16x16x32_bf16 v[190:193], v[234:237], v[12:15], v[112:115]
	ds_read_b128 v[234:237], v217 offset:64
	s_waitcnt lgkmcnt(5)
	v_mfma_f32_16x16x32_bf16 v[132:135], v[242:245], v[8:11], v[128:131]
	ds_read_b128 v[242:245], v217 offset:192
	s_waitcnt lgkmcnt(5)
	v_mfma_f32_16x16x32_bf16 v[194:197], v[246:249], v[12:15], v[112:115]
	ds_read_b128 v[246:249], v217 offset:4672
	s_waitcnt lgkmcnt(5)
	v_mfma_f32_16x16x32_bf16 v[198:201], v[204:207], v[8:11], v[128:131]
	ds_read_b128 v[204:207], v217 offset:4800
	s_waitcnt lgkmcnt(5)
	v_mfma_f32_16x16x32_bf16 v[112:115], v[226:229], v[12:15], v[112:115]
	ds_read_b128 v[226:229], v217 offset:9280
	s_waitcnt lgkmcnt(5)
	v_mfma_f32_16x16x32_bf16 v[218:221], v[230:233], v[8:11], v[128:131]
	ds_read_b128 v[230:233], v217 offset:9408
	s_waitcnt lgkmcnt(5)
	v_mfma_f32_16x16x32_bf16 v[140:143], v[234:237], v[4:7], v[116:119]
	ds_read_b128 v[234:237], v217 offset:13888
	s_waitcnt lgkmcnt(5)
	v_mfma_f32_16x16x32_bf16 v[124:127], v[242:245], v[0:3], v[120:123]
	ds_read_b128 v[242:245], v217 offset:14016
	s_waitcnt lgkmcnt(5)
	v_mfma_f32_16x16x32_bf16 v[136:139], v[246:249], v[4:7], v[190:193]
	s_waitcnt lgkmcnt(4)
	v_mfma_f32_16x16x32_bf16 v[120:123], v[204:207], v[0:3], v[132:135]
	s_waitcnt lgkmcnt(3)
	v_mfma_f32_16x16x32_bf16 v[132:135], v[226:229], v[4:7], v[194:197]
	s_waitcnt lgkmcnt(2)
	v_mfma_f32_16x16x32_bf16 v[116:119], v[230:233], v[0:3], v[198:201]
	s_waitcnt lgkmcnt(1)
	v_mfma_f32_16x16x32_bf16 v[128:131], v[234:237], v[4:7], v[112:115]
	s_waitcnt lgkmcnt(0)
	v_mfma_f32_16x16x32_bf16 v[112:115], v[242:245], v[0:3], v[218:221]
	v_max_f32_e32 v190, v141, v141
	v_max_f32_e32 v191, v140, v140
	v_max_f32_e32 v204, v125, v125
	v_max_f32_e32 v205, v124, v124
	v_max_f32_e32 v190, v191, v190
	v_max_f32_e32 v204, v205, v204
	v_max3_f32 v190, v190, v142, v143
	v_max3_f32 v204, v204, v126, v127
	v_max3_f32 v190, v190, v136, v137
	v_max3_f32 v204, v204, v120, v121
	v_max3_f32 v190, v190, v138, v139
	v_max3_f32 v204, v204, v122, v123
	v_max3_f32 v190, v190, v132, v133
	v_max3_f32 v204, v204, v116, v117
	v_max3_f32 v190, v190, v134, v135
	v_max3_f32 v204, v204, v118, v119
	v_max3_f32 v190, v190, v128, v129
	v_max3_f32 v204, v204, v112, v113
	v_max3_f32 v190, v190, v130, v131
	v_max3_f32 v204, v204, v114, v115
	v_mov_b32_e32 v191, v190
	v_mov_b32_e32 v205, v204
	s_nop 1
	v_permlane16_swap_b32_e32 v191, v190
	v_permlane16_swap_b32_e32 v205, v204
	v_max_f32_e32 v190, v190, v191
	v_max_f32_e32 v204, v204, v205
	v_mov_b32_e32 v191, v190
	v_mov_b32_e32 v205, v204
	s_nop 1
	v_permlane32_swap_b32_e32 v191, v190
	v_permlane32_swap_b32_e32 v205, v204
	v_max_f32_e32 v217, v190, v191
	v_max_f32_e32 v206, v204, v205
	v_cmp_lt_f32_e32 vcc, s79, v217
	s_cbranch_vccz .LBB0_1042
	s_nop 0
	v_cndmask_b32_e32 v191, 0, v217, vcc
	v_exp_f32_e64 v190, -v191
	v_add_f32_e32 v213, v213, v191
	v_sub_f32_e32 v140, v140, v191
	v_sub_f32_e32 v141, v141, v191
	v_pk_mul_f32 v[30:31], v[30:31], v[190:191] op_sel_hi:[1,0]
	v_pk_mul_f32 v[28:29], v[28:29], v[190:191] op_sel_hi:[1,0]
	v_pk_mul_f32 v[42:43], v[42:43], v[190:191] op_sel_hi:[1,0]
	v_pk_mul_f32 v[40:41], v[40:41], v[190:191] op_sel_hi:[1,0]
	v_pk_mul_f32 v[70:71], v[70:71], v[190:191] op_sel_hi:[1,0]
	v_pk_mul_f32 v[68:69], v[68:69], v[190:191] op_sel_hi:[1,0]
	v_pk_mul_f32 v[78:79], v[78:79], v[190:191] op_sel_hi:[1,0]
	v_pk_mul_f32 v[76:77], v[76:77], v[190:191] op_sel_hi:[1,0]
	v_pk_mul_f32 v[86:87], v[86:87], v[190:191] op_sel_hi:[1,0]
	v_pk_mul_f32 v[84:85], v[84:85], v[190:191] op_sel_hi:[1,0]
	v_pk_mul_f32 v[94:95], v[94:95], v[190:191] op_sel_hi:[1,0]
	v_pk_mul_f32 v[92:93], v[92:93], v[190:191] op_sel_hi:[1,0]
	v_pk_mul_f32 v[102:103], v[102:103], v[190:191] op_sel_hi:[1,0]
	v_pk_mul_f32 v[100:101], v[100:101], v[190:191] op_sel_hi:[1,0]
	v_pk_mul_f32 v[110:111], v[110:111], v[190:191] op_sel_hi:[1,0]
	v_pk_mul_f32 v[108:109], v[108:109], v[190:191] op_sel_hi:[1,0]
	v_mul_f32_e32 v171, v171, v190
	v_sub_f32_e32 v142, v142, v191
	v_sub_f32_e32 v143, v143, v191
	v_sub_f32_e32 v136, v136, v191
	v_sub_f32_e32 v137, v137, v191
	v_sub_f32_e32 v138, v138, v191
	v_sub_f32_e32 v139, v139, v191
	v_sub_f32_e32 v132, v132, v191
	v_sub_f32_e32 v133, v133, v191
	v_sub_f32_e32 v134, v134, v191
	v_sub_f32_e32 v135, v135, v191
	v_sub_f32_e32 v128, v128, v191
	v_sub_f32_e32 v129, v129, v191
	v_sub_f32_e32 v130, v130, v191
	v_sub_f32_e32 v131, v131, v191
